# final rmsnorm output stores without the nt hint (plain write-back stores)
# speedup vs baseline: 1.0063x; 1.0063x over previous
; DI void ph_final(const Params& p, int bid, int nb) {
;     ...
; #pragma unroll
;     for (int rr = 0; rr < 2; ++rr) {
;       float* rp = p.out + (size_t)(it * 8 + rr * 4 + w) * DM;
;       float ss = 0.f;
; #pragma unroll
;       for (int i = 0; i < 4; ++i) ss += v[rr][i].x * v[rr][i].x + v[rr][i].y * v[rr][i].y + v[rr][i].z * v[rr][i].z + v[rr][i].w * v[rr][i].w;
;       ss = wave_sum(ss);
;       const float rstd = rsqrtf(ss * (1.f / DM) + EPS);
; #pragma unroll
;       for (int i = 0; i < 4; ++i) {
;         const int j = (i * 64 + lane) * 4;
;         const float4 gg = *(const float4*)(p.final_g + j);
;         float4 o;
;         o.x = v[rr][i].x * rstd * gg.x; o.y = v[rr][i].y * rstd * gg.y; o.z = v[rr][i].z * rstd * gg.z; o.w = v[rr][i].w * rstd * gg.w;
;         {
;           typedef float f32x4_t __attribute__((ext_vector_type(4)));
;           const f32x4_t ov = {o.x, o.y, o.z, o.w};
;           __builtin_nontemporal_store(ov, (f32x4_t*)(rp + j));
;         }
;       }
.Lfn_nopf:
	v_mov_b32_e32 v56, v17
	v_mov_b32_e32 v57, v21
	v_mov_b32_e32 v64, v25
	v_mov_b32_e32 v65, v29
	v_mov_b32_e32 v54, v16
	v_mov_b32_e32 v55, v20
	v_mov_b32_e32 v62, v24
	v_mov_b32_e32 v63, v28
	v_pk_mul_f32 v[56:57], v[56:57], v[56:57]
	v_pk_mul_f32 v[64:65], v[64:65], v[64:65]
	v_mov_b32_e32 v72, v33
	v_mov_b32_e32 v73, v37
	v_mov_b32_e32 v58, v18
	v_mov_b32_e32 v59, v22
	v_mov_b32_e32 v70, v32
	v_mov_b32_e32 v71, v36
	v_mov_b32_e32 v80, v41
	v_mov_b32_e32 v81, v45
	v_pk_fma_f32 v[54:55], v[54:55], v[54:55], v[56:57]
	v_pk_fma_f32 v[56:57], v[62:63], v[62:63], v[64:65]
	v_pk_mul_f32 v[62:63], v[72:73], v[72:73]
	v_mov_b32_e32 v74, v34
	v_mov_b32_e32 v75, v38
	v_mov_b32_e32 v78, v40
	v_mov_b32_e32 v79, v44
	v_pk_mul_f32 v[64:65], v[80:81], v[80:81]
	v_pk_fma_f32 v[54:55], v[58:59], v[58:59], v[54:55]
	v_pk_fma_f32 v[58:59], v[70:71], v[70:71], v[62:63]
	v_mov_b32_e32 v60, v19
	v_mov_b32_e32 v61, v23
	v_mov_b32_e32 v66, v26
	v_mov_b32_e32 v67, v30
	v_mov_b32_e32 v76, v35
	v_mov_b32_e32 v77, v39
	v_mov_b32_e32 v82, v42
	v_mov_b32_e32 v83, v46
	v_pk_fma_f32 v[62:63], v[78:79], v[78:79], v[64:65]
	v_pk_fma_f32 v[58:59], v[74:75], v[74:75], v[58:59]
	v_mov_b32_e32 v68, v27
	v_mov_b32_e32 v69, v31
	v_mov_b32_e32 v84, v43
	v_mov_b32_e32 v85, v47
	v_pk_fma_f32 v[56:57], v[66:67], v[66:67], v[56:57]
	v_pk_fma_f32 v[54:55], v[60:61], v[60:61], v[54:55]
	v_pk_fma_f32 v[60:61], v[82:83], v[82:83], v[62:63]
	v_pk_fma_f32 v[58:59], v[76:77], v[76:77], v[58:59]
	v_pk_fma_f32 v[56:57], v[68:69], v[68:69], v[56:57]
	v_pk_fma_f32 v[60:61], v[84:85], v[84:85], v[60:61]
	v_mov_b32_e32 v63, v54
	v_mov_b32_e32 v62, v58
	v_mov_b32_e32 v54, v59
	v_mov_b32_e32 v65, v56
	v_mov_b32_e32 v64, v60
	v_pk_add_f32 v[54:55], v[62:63], v[54:55]
	v_mov_b32_e32 v56, v61
	v_pk_add_f32 v[54:55], v[54:55], v[64:65]
	s_nop 0
	v_pk_add_f32 v[54:55], v[54:55], v[56:57]
	v_mov_b32_e32 v56, v54
	v_mov_b32_e32 v57, v55
	s_nop 1
	v_permlane32_swap_b32_e32 v56, v54
	v_permlane32_swap_b32_e32 v57, v55
	v_pk_add_f32 v[54:55], v[54:55], v[56:57]
	v_mov_b32_e32 v56, v54
	v_mov_b32_e32 v57, v55
	s_nop 1
	v_permlane16_swap_b32_e32 v56, v54
	v_permlane16_swap_b32_e32 v57, v55
	v_pk_add_f32 v[54:55], v[54:55], v[56:57]
	s_nop 1
	v_add_f32_dpp v54, v54, v54 row_ror:8 row_mask:0xf bank_mask:0xf
	v_add_f32_dpp v55, v55, v55 row_ror:8 row_mask:0xf bank_mask:0xf
	s_nop 0
	v_add_f32_dpp v56, v54, v54 row_shl:4 row_mask:0xf bank_mask:0x5
	v_add_f32_dpp v57, v55, v55 row_shl:4 row_mask:0xf bank_mask:0x5
	v_add_f32_dpp v56, v54, v54 row_shr:4 row_mask:0xf bank_mask:0xa
	v_add_f32_dpp v57, v55, v55 row_shr:4 row_mask:0xf bank_mask:0xa
	s_nop 0
	v_add_f32_dpp v54, v56, v56 quad_perm:[2,3,0,1] row_mask:0xf bank_mask:0xf
	v_add_f32_dpp v55, v57, v57 quad_perm:[2,3,0,1] row_mask:0xf bank_mask:0xf
	s_nop 0
	v_add_f32_dpp v54, v54, v54 quad_perm:[1,0,3,2] row_mask:0xf bank_mask:0xf
	v_add_f32_dpp v55, v55, v55 quad_perm:[1,0,3,2] row_mask:0xf bank_mask:0xf
	s_nop 0
	v_pk_fma_f32 v[54:55], v[54:55], s[0:1], v[6:7] op_sel_hi:[1,0,0]
	s_nop 0
	v_mul_f32_e32 v5, 0x4b800000, v55
	v_cmp_gt_f32_e32 vcc, s1, v55
	s_nop 1
	v_cndmask_b32_e32 v5, v55, v5, vcc
	v_rsq_f32_e32 v5, v5
	s_nop 0
	v_mul_f32_e32 v15, 0x45800000, v5
	v_cndmask_b32_e32 v56, v5, v15, vcc
	v_pk_mul_f32 v[16:17], v[16:17], v[56:57] op_sel_hi:[1,0]
	v_pk_mul_f32 v[18:19], v[18:19], v[56:57] op_sel_hi:[1,0]
	v_pk_mul_f32 v[16:17], v[86:87], v[16:17]
	v_pk_mul_f32 v[18:19], v[88:89], v[18:19]
	global_store_dwordx4 v[52:53], v[16:19], off
	v_pk_mul_f32 v[22:23], v[22:23], v[56:57] op_sel_hi:[1,0]
	v_pk_mul_f32 v[20:21], v[20:21], v[56:57] op_sel_hi:[1,0]
	v_mul_f32_e32 v5, 0x4b800000, v54
	v_cmp_gt_f32_e32 vcc, s1, v54
	v_pk_mul_f32 v[16:17], v[90:91], v[20:21]
	v_pk_mul_f32 v[18:19], v[92:93], v[22:23]
	global_store_dwordx4 v[52:53], v[16:19], off offset:1024
	v_pk_mul_f32 v[20:21], v[26:27], v[56:57] op_sel_hi:[1,0]
	v_pk_mul_f32 v[22:23], v[24:25], v[56:57] op_sel_hi:[1,0]
	v_cndmask_b32_e32 v5, v54, v5, vcc
	v_rsq_f32_e32 v5, v5
	v_pk_mul_f32 v[16:17], v[22:23], v[94:95]
	v_pk_mul_f32 v[18:19], v[20:21], v[96:97]
	global_store_dwordx4 v[52:53], v[16:19], off offset:2048
	v_pk_mul_f32 v[20:21], v[30:31], v[56:57] op_sel_hi:[1,0]
	v_pk_mul_f32 v[22:23], v[28:29], v[56:57] op_sel_hi:[1,0]
	v_mul_f32_e32 v15, 0x45800000, v5
	v_pk_mul_f32 v[16:17], v[22:23], v[98:99]
	v_pk_mul_f32 v[18:19], v[20:21], v[100:101]
	global_store_dwordx4 v[52:53], v[16:19], off offset:3072
	v_cndmask_b32_e32 v20, v5, v15, vcc
	v_pk_mul_f32 v[22:23], v[34:35], v[20:21] op_sel_hi:[1,0]
	v_pk_mul_f32 v[24:25], v[32:33], v[20:21] op_sel_hi:[1,0]
	v_pk_mul_f32 v[18:19], v[88:89], v[22:23]
	v_pk_mul_f32 v[16:17], v[86:87], v[24:25]
	global_store_dwordx4 v[8:9], v[16:19], off
	v_pk_mul_f32 v[22:23], v[38:39], v[20:21] op_sel_hi:[1,0]
	v_pk_mul_f32 v[24:25], v[36:37], v[20:21] op_sel_hi:[1,0]
	v_pk_mul_f32 v[18:19], v[92:93], v[22:23]
	v_pk_mul_f32 v[16:17], v[90:91], v[24:25]
	global_store_dwordx4 v[8:9], v[16:19], off offset:1024
	v_pk_mul_f32 v[22:23], v[42:43], v[20:21] op_sel_hi:[1,0]
	v_pk_mul_f32 v[24:25], v[40:41], v[20:21] op_sel_hi:[1,0]
	v_pk_mul_f32 v[18:19], v[22:23], v[96:97]
	v_pk_mul_f32 v[16:17], v[24:25], v[94:95]
	global_store_dwordx4 v[8:9], v[16:19], off offset:2048
	v_pk_mul_f32 v[22:23], v[46:47], v[20:21] op_sel_hi:[1,0]
	v_pk_mul_f32 v[20:21], v[44:45], v[20:21] op_sel_hi:[1,0]
	v_pk_mul_f32 v[18:19], v[22:23], v[100:101]
	v_pk_mul_f32 v[16:17], v[20:21], v[98:99]
	global_store_dwordx4 v[8:9], v[16:19], off offset:3072
	s_cbranch_scc1 .LBB0_1133
